# E5 nsa compressed-branch loops run at priority 0 (were raised to 1 until the next barrier), so the co-resident block's selected-branch tiles win issue arbitration
# speedup vs baseline: 1.0055x; 1.0055x over previous
.LBB0_883:
	s_add_i32 s39, s41, 1
	v_mov_b32_e32 v36, v2
	s_waitcnt vmcnt(3)
	v_mov_b64_e32 v[2:3], v[50:51]
	s_cmp_lt_u32 s41, s15
	v_mov_b64_e32 v[4:5], v[52:53]
	s_cselect_b32 s41, s2, 0
	v_or_b32_e32 v6, s41, v93
	v_ashrrev_i32_e32 v7, 31, v6
	v_lshlrev_b64 v[6:7], 7, v[6:7]
	s_waitcnt vmcnt(0)
	v_mov_b64_e32 v[24:25], v[62:63]
	v_mov_b64_e32 v[28:29], v[58:59]
	v_mov_b64_e32 v[32:33], v[54:55]
	v_lshl_add_u64 v[6:7], v[82:83], 0, v[6:7]
	v_mov_b64_e32 v[26:27], v[64:65]
	v_mov_b64_e32 v[30:31], v[60:61]
	v_mov_b64_e32 v[34:35], v[56:57]
	global_load_dwordx4 v[50:53], v[6:7], off
	global_load_dwordx4 v[54:57], v[6:7], off offset:16
	global_load_dwordx4 v[58:61], v[6:7], off offset:32
	global_load_dwordx4 v[62:65], v[6:7], off offset:48
	s_setprio 0
	v_mfma_f32_32x32x16_bf16 v[2:17], v[2:5], v[130:133], 0
	s_add_i32 s2, s2, 32
	s_mov_b32 s41, s39
	v_mfma_f32_32x32x16_bf16 v[2:17], v[32:35], v[134:137], v[2:17]
	v_mfma_f32_32x32x16_bf16 v[2:17], v[28:31], v[138:141], v[2:17]
	v_mfma_f32_32x32x16_bf16 v[2:17], v[24:27], v[142:145], v[2:17]
	v_add_u32_e32 v24, s3, v20
	v_cmp_le_i32_e32 vcc, v24, v22
	v_add_u32_e32 v25, 16, v24
	v_add_u32_e32 v26, 32, v24
	s_addk_i32 s3, 0x200
	s_cmp_eq_u32 s38, s3
	s_nop 5
	v_mul_f32_e32 v2, 0x3e38aa3b, v2
	v_cndmask_b32_e32 v2, v220, v2, vcc
	v_mul_f32_e32 v3, 0x3e38aa3b, v3
	v_cmp_le_i32_e32 vcc, v25, v22
	v_mul_f32_e32 v4, 0x3e38aa3b, v4
	v_mul_f32_e32 v5, 0x3e38aa3b, v5
	v_cndmask_b32_e32 v3, v220, v3, vcc
	v_cmp_le_i32_e32 vcc, v26, v22
	v_add_u32_e32 v26, 48, v24
	v_mul_f32_e32 v6, 0x3e38aa3b, v6
	v_cndmask_b32_e32 v4, v220, v4, vcc
	v_cmp_le_i32_e32 vcc, v26, v22
	v_add_u32_e32 v26, 64, v24
	v_mul_f32_e32 v7, 0x3e38aa3b, v7
	v_cndmask_b32_e32 v5, v220, v5, vcc
	v_cmp_le_i32_e32 vcc, v26, v22
	v_add_u32_e32 v26, 0x50, v24
	v_mul_f32_e32 v8, 0x3e38aa3b, v8
	v_cndmask_b32_e32 v6, v220, v6, vcc
	v_cmp_le_i32_e32 vcc, v26, v22
	v_add_u32_e32 v26, 0x60, v24
	v_mul_f32_e32 v9, 0x3e38aa3b, v9
	v_cndmask_b32_e32 v7, v220, v7, vcc
	v_cmp_le_i32_e32 vcc, v26, v22
	v_add_u32_e32 v26, 0x70, v24
	v_mul_f32_e32 v10, 0x3e38aa3b, v10
	v_cndmask_b32_e32 v8, v220, v8, vcc
	v_cmp_le_i32_e32 vcc, v26, v22
	v_add_u32_e32 v26, 0x100, v24
	v_mul_f32_e32 v11, 0x3e38aa3b, v11
	v_cndmask_b32_e32 v9, v220, v9, vcc
	v_cmp_le_i32_e32 vcc, v26, v22
	v_add_u32_e32 v26, 0x110, v24
	v_max3_f32 v25, v2, s85, v3
	v_cndmask_b32_e32 v10, v220, v10, vcc
	v_cmp_le_i32_e32 vcc, v26, v22
	v_add_u32_e32 v26, 0x120, v24
	v_mul_f32_e32 v12, 0x3e38aa3b, v12
	v_cndmask_b32_e32 v11, v220, v11, vcc
	v_cmp_le_i32_e32 vcc, v26, v22
	v_add_u32_e32 v26, 0x130, v24
	v_max3_f32 v25, v25, v4, v5
	v_cndmask_b32_e32 v12, v220, v12, vcc
	v_mul_f32_e32 v13, 0x3e38aa3b, v13
	v_cmp_le_i32_e32 vcc, v26, v22
	v_add_u32_e32 v26, 0x140, v24
	v_max3_f32 v25, v25, v6, v7
	v_cndmask_b32_e32 v13, v220, v13, vcc
	v_mul_f32_e32 v14, 0x3e38aa3b, v14
	v_cmp_le_i32_e32 vcc, v26, v22
	v_add_u32_e32 v26, 0x150, v24
	v_max3_f32 v25, v25, v8, v9
	v_cndmask_b32_e32 v14, v220, v14, vcc
	v_mul_f32_e32 v15, 0x3e38aa3b, v15
	v_cmp_le_i32_e32 vcc, v26, v22
	v_add_u32_e32 v26, 0x160, v24
	v_max3_f32 v25, v25, v10, v11
	v_cndmask_b32_e32 v15, v220, v15, vcc
	v_mul_f32_e32 v16, 0x3e38aa3b, v16
	v_cmp_le_i32_e32 vcc, v26, v22
	v_add_u32_e32 v24, 0x170, v24
	v_max3_f32 v25, v25, v12, v13
	v_cndmask_b32_e32 v16, v220, v16, vcc
	v_mul_f32_e32 v17, 0x3e38aa3b, v17
	v_cmp_le_i32_e32 vcc, v24, v22
	v_max3_f32 v25, v25, v14, v15
	s_nop 0
	v_cndmask_b32_e32 v17, v220, v17, vcc
	v_max3_f32 v24, v25, v16, v17
	ds_bpermute_b32 v25, v167, v24
	s_waitcnt lgkmcnt(0)
	v_max3_f32 v24, v23, v24, v25
	v_cmp_neq_f32_e32 vcc, s85, v24
	s_nop 1
	v_cndmask_b32_e32 v96, 0, v24, vcc
	v_sub_f32_e32 v2, v2, v96
	v_exp_f32_e32 v2, v2
	v_sub_f32_e32 v3, v3, v96
	v_exp_f32_e32 v3, v3
	v_sub_f32_e32 v23, v23, v96
	v_add_f32_e32 v2, 0, v2
	v_add_f32_e32 v2, v3, v2
	v_sub_f32_e32 v3, v4, v96
	v_exp_f32_e32 v3, v3
	s_nop 0
	v_add_f32_e32 v2, v3, v2
	v_sub_f32_e32 v3, v5, v96
	v_exp_f32_e32 v3, v3
	s_nop 0
	v_add_f32_e32 v2, v3, v2
	v_sub_f32_e32 v3, v6, v96
	v_exp_f32_e32 v3, v3
	s_nop 0
	v_add_f32_e32 v2, v3, v2
	v_sub_f32_e32 v3, v7, v96
	v_exp_f32_e32 v3, v3
	s_nop 0
	v_add_f32_e32 v2, v3, v2
	v_sub_f32_e32 v3, v8, v96
	v_exp_f32_e32 v3, v3
	s_nop 0
	v_add_f32_e32 v2, v3, v2
	v_sub_f32_e32 v3, v9, v96
	v_exp_f32_e32 v3, v3
	s_nop 0
	v_add_f32_e32 v2, v3, v2
	v_sub_f32_e32 v3, v10, v96
	v_exp_f32_e32 v3, v3
	s_nop 0
	v_add_f32_e32 v2, v3, v2
	v_sub_f32_e32 v3, v11, v96
	v_exp_f32_e32 v3, v3
	s_nop 0
	v_add_f32_e32 v2, v3, v2
	v_sub_f32_e32 v3, v12, v96
	v_exp_f32_e32 v3, v3
	s_nop 0
	v_add_f32_e32 v2, v3, v2
	v_sub_f32_e32 v3, v13, v96
	v_exp_f32_e32 v3, v3
	s_nop 0
	v_add_f32_e32 v2, v3, v2
	v_sub_f32_e32 v3, v14, v96
	v_exp_f32_e32 v3, v3
	s_nop 0
	v_add_f32_e32 v2, v3, v2
	v_sub_f32_e32 v3, v15, v96
	v_exp_f32_e32 v3, v3
	s_nop 0
	v_add_f32_e32 v2, v3, v2
	v_sub_f32_e32 v3, v16, v96
	v_exp_f32_e32 v3, v3
	s_nop 0
	v_add_f32_e32 v2, v3, v2
	v_sub_f32_e32 v3, v17, v96
	v_exp_f32_e32 v3, v3
	s_nop 0
	v_add_f32_e32 v2, v3, v2
	v_exp_f32_e32 v3, v23
	v_mov_b32_e32 v23, v24
	v_fmac_f32_e32 v2, v36, v3
	s_cbranch_scc0 .LBB0_883
	ds_bpermute_b32 v3, v167, v2
	v_lshlrev_b32_e32 v166, 3, v21
	v_add_u32_e32 v98, 0x18f, v20
	v_lshl_or_b32 v84, v92, 8, v223
	v_mov_b32_e32 v85, v1
	s_waitcnt lgkmcnt(0)
	v_add_f32_e32 v3, v2, v3
	v_div_scale_f32 v4, s[2:3], v3, v3, 1.0
	v_rcp_f32_e32 v5, v4
	v_div_scale_f32 v6, vcc, 1.0, v3, 1.0
	s_add_u32 s2, s18, s22
	v_fma_f32 v7, -v4, v5, 1.0
	v_fmac_f32_e32 v5, v7, v5
	v_mul_f32_e32 v7, v6, v5
	v_fma_f32 v8, -v4, v7, v6
	v_fmac_f32_e32 v7, v8, v5
	v_fma_f32 v4, -v4, v7, v6
	v_div_fmas_f32 v4, v4, v5, v7
	v_div_fixup_f32 v4, v4, v3, 1.0
	v_cmp_lt_f32_e32 vcc, 0, v3
	v_lshlrev_b32_e32 v3, 12, v18
	v_mov_b32_e32 v2, 0
	v_cndmask_b32_e32 v97, 0, v4, vcc
	v_lshlrev_b32_e32 v4, 7, v91
	v_or3_b32 v99, v3, v4, v166
	v_and_b32_e32 v4, 16, v19
	v_mov_b32_e32 v5, v1
	s_addc_u32 s3, s19, s23
	v_lshl_add_u64 v[86:87], s[2:3], 0, v[4:5]
	v_lshlrev_b32_e32 v88, 8, v91
	v_mov_b32_e32 v89, v1
	s_mov_b32 s22, 0
	v_mov_b32_e32 v3, v2
	v_mov_b32_e32 v4, v2
	v_mov_b32_e32 v5, v2
	v_mov_b32_e32 v6, v2
	v_mov_b32_e32 v7, v2
	v_mov_b32_e32 v8, v2
	v_mov_b32_e32 v9, v2
	v_mov_b32_e32 v10, v2
	v_mov_b32_e32 v11, v2
	v_mov_b32_e32 v12, v2
	v_mov_b32_e32 v13, v2
	v_mov_b32_e32 v14, v2
	v_mov_b32_e32 v15, v2
	v_mov_b32_e32 v16, v2
	v_mov_b32_e32 v17, v2
	v_mov_b32_e32 v18, v2
	v_mov_b32_e32 v19, v2
	v_mov_b32_e32 v20, v2
	v_mov_b32_e32 v21, v2
	v_mov_b32_e32 v22, v2
	v_mov_b32_e32 v23, v2
	v_mov_b32_e32 v24, v2
	v_mov_b32_e32 v25, v2
	v_mov_b32_e32 v26, v2
	v_mov_b32_e32 v27, v2
	v_mov_b32_e32 v28, v2
	v_mov_b32_e32 v29, v2
	v_mov_b32_e32 v30, v2
	v_mov_b32_e32 v31, v2
	v_mov_b32_e32 v32, v2
	v_mov_b32_e32 v33, v2
	s_branch .LBB0_886
.LBB0_885:
	s_or_b64 exec, exec, s[2:3]
	v_cvt_pk_bf16_f32 v103, v40, v42
	v_cvt_pk_bf16_f32 v102, v38, v39
	v_cvt_pk_bf16_f32 v101, v36, v37
	v_cvt_pk_bf16_f32 v100, v34, v35
	v_cvt_pk_bf16_f32 v37, v48, v49
	v_cvt_pk_bf16_f32 v36, v46, v47
	s_waitcnt vmcnt(5)
	s_setprio 0
	v_mfma_f32_32x32x16_bf16 v[2:17], v[74:77], v[100:103], v[2:17]
	v_cvt_pk_bf16_f32 v35, v44, v45
	v_cvt_pk_bf16_f32 v34, v41, v43
	v_add_u32_e32 v98, 0x200, v98
	v_add_u32_e32 v99, 32, v99
	v_lshl_add_u64 v[86:87], v[86:87], 0, 64
	s_cmp_eq_u32 s22, s15
	s_mov_b32 s22, s23
	s_waitcnt vmcnt(3)
	v_mfma_f32_32x32x16_bf16 v[18:33], v[78:81], v[100:103], v[18:33]
	v_mfma_f32_32x32x16_bf16 v[2:17], v[70:73], v[34:37], v[2:17]
	s_waitcnt vmcnt(2)
	v_mfma_f32_32x32x16_bf16 v[18:33], v[66:69], v[34:37], v[18:33]
	s_cbranch_scc1 .LBB0_888
.LBB0_886:
	s_waitcnt vmcnt(3)
	s_setprio 0
	v_mfma_f32_32x32x16_bf16 v[34:49], v[50:53], v[130:133], 0
	s_waitcnt vmcnt(2)
	v_mov_b64_e32 v[68:69], v[56:57]
	v_mov_b64_e32 v[66:67], v[54:55]
	s_add_i32 s23, s22, 1
	s_cmp_lt_u32 s22, s15
	s_cselect_b32 s2, s23, s22
	v_lshl_or_b32 v50, s2, 5, v95
	v_ashrrev_i32_e32 v51, 31, v50
	v_mfma_f32_32x32x16_bf16 v[34:49], v[66:69], v[134:137], v[34:49]
	v_lshl_add_u64 v[70:71], v[86:87], 0, v[88:89]
	v_lshlrev_b64 v[50:51], 7, v[50:51]
	v_add_co_u32_e32 v66, vcc, s97, v70
	v_lshl_add_u64 v[100:101], v[82:83], 0, v[50:51]
	s_nop 0
	v_addc_co_u32_e32 v67, vcc, 0, v71, vcc
	s_waitcnt vmcnt(1)
	v_mfma_f32_32x32x16_bf16 v[34:49], v[58:61], v[138:141], v[34:49]
	global_load_dwordx4 v[50:53], v[100:101], off
	global_load_dwordx4 v[54:57], v[100:101], off offset:16
	global_load_dwordx4 v[74:77], v[66:67], off
	global_load_dwordx4 v[70:73], v[66:67], off offset:32
	v_lshl_add_u64 v[66:67], v[86:87], 0, v[84:85]
	v_add_co_u32_e32 v58, vcc, s97, v66
	v_add_u32_e32 v102, 0xfffffe90, v98
	s_nop 0
	v_addc_co_u32_e32 v59, vcc, 0, v67, vcc
	global_load_dwordx4 v[78:81], v[58:59], off
	global_load_dwordx4 v[66:69], v[58:59], off offset:32
	s_waitcnt vmcnt(6)
	v_mfma_f32_32x32x16_bf16 v[34:49], v[62:65], v[142:145], v[34:49]
	global_load_dwordx4 v[58:61], v[100:101], off offset:32
	global_load_dwordx4 v[62:65], v[100:101], off offset:48
	v_add_u32_e32 v103, 0xfffffea0, v98
	v_cmp_le_u32_e32 vcc, v102, v94
	v_add_u32_e32 v100, 0xfffffeb0, v98
	s_movk_i32 s2, 0x80f
	s_nop 5
	v_fma_f32 v34, v34, s86, -v96
	v_fma_f32 v35, v35, s86, -v96
	v_exp_f32_e32 v34, v34
	v_exp_f32_e32 v35, v35
	v_fma_f32 v36, v36, s86, -v96
	v_exp_f32_e32 v36, v36
	v_fma_f32 v37, v37, s86, -v96
	v_exp_f32_e32 v37, v37
	v_fma_f32 v38, v38, s86, -v96
	v_mul_f32_e32 v34, v97, v34
	v_exp_f32_e32 v38, v38
	v_fma_f32 v39, v39, s86, -v96
	v_mul_f32_e32 v35, v97, v35
	v_cndmask_b32_e32 v34, 0, v34, vcc
	v_cmp_le_u32_e32 vcc, v103, v94
	v_exp_f32_e32 v39, v39
	v_fma_f32 v40, v40, s86, -v96
	v_cndmask_b32_e32 v35, 0, v35, vcc
	v_mul_f32_e32 v36, v97, v36
	v_cmp_le_u32_e32 vcc, v100, v94
	v_add_u32_e32 v100, 0xfffffec0, v98
	v_exp_f32_e32 v40, v40
	v_fma_f32 v41, v41, s86, -v96
	v_cndmask_b32_e32 v36, 0, v36, vcc
	v_mul_f32_e32 v37, v97, v37
	v_cmp_le_u32_e32 vcc, v100, v94
	v_add_u32_e32 v100, 0xfffffed0, v98
	v_exp_f32_e32 v41, v41
	v_cndmask_b32_e32 v37, 0, v37, vcc
	v_mul_f32_e32 v38, v97, v38
	v_cmp_le_u32_e32 vcc, v100, v94
	v_add_u32_e32 v100, 0xfffffee0, v98
	v_fma_f32 v42, v42, s86, -v96
	v_cndmask_b32_e32 v38, 0, v38, vcc
	v_mul_f32_e32 v39, v97, v39
	v_cmp_le_u32_e32 vcc, v100, v94
	v_add_u32_e32 v100, 0xfffffef0, v98
	v_exp_f32_e32 v101, v42
	v_cndmask_b32_e32 v39, 0, v39, vcc
	v_mul_f32_e32 v40, v97, v40
	v_cmp_le_u32_e32 vcc, v100, v94
	v_add_u32_e32 v100, 0xffffff00, v98
	v_fma_f32 v43, v43, s86, -v96
	v_cndmask_b32_e32 v40, 0, v40, vcc
	v_mul_f32_e32 v41, v97, v41
	v_cmp_le_u32_e32 vcc, v100, v94
	v_exp_f32_e32 v43, v43
	v_fma_f32 v44, v44, s86, -v96
	v_cndmask_b32_e32 v42, 0, v41, vcc
	v_add_u32_e32 v41, 0xffffff90, v98
	v_exp_f32_e32 v44, v44
	v_fma_f32 v45, v45, s86, -v96
	v_mul_f32_e32 v100, v97, v101
	v_cmp_le_u32_e32 vcc, v41, v94
	v_exp_f32_e32 v45, v45
	v_fma_f32 v46, v46, s86, -v96
	v_cndmask_b32_e32 v41, 0, v100, vcc
	v_add_u32_e32 v100, 0xffffffa0, v98
	v_exp_f32_e32 v46, v46
	v_fma_f32 v47, v47, s86, -v96
	v_mul_f32_e32 v43, v97, v43
	v_cmp_le_u32_e32 vcc, v100, v94
	v_add_u32_e32 v100, 0xffffffb0, v98
	v_exp_f32_e32 v47, v47
	v_cndmask_b32_e32 v43, 0, v43, vcc
	v_mul_f32_e32 v44, v97, v44
	v_cmp_le_u32_e32 vcc, v100, v94
	v_subrev_u32_e32 v100, 64, v98
	v_mul_f32_e32 v45, v97, v45
	v_cndmask_b32_e32 v44, 0, v44, vcc
	v_cmp_le_u32_e32 vcc, v100, v94
	v_subrev_u32_e32 v100, 48, v98
	v_mul_f32_e32 v46, v97, v46
	v_cndmask_b32_e32 v45, 0, v45, vcc
	v_cmp_le_u32_e32 vcc, v100, v94
	v_subrev_u32_e32 v100, 32, v98
	v_fma_f32 v48, v48, s86, -v96
	v_cndmask_b32_e32 v46, 0, v46, vcc
	v_mul_f32_e32 v47, v97, v47
	v_cmp_le_u32_e32 vcc, v100, v94
	v_exp_f32_e32 v48, v48
	v_add_u32_e32 v100, -16, v98
	v_fma_f32 v49, v49, s86, -v96
	v_add_f32_e32 v101, v37, v38
	v_cndmask_b32_e32 v47, 0, v47, vcc
	v_exp_f32_e32 v49, v49
	v_cmp_le_u32_e32 vcc, v100, v94
	v_add_f32_e32 v100, v34, v35
	v_add_f32_e32 v101, v39, v101
	v_add_f32_e32 v100, v36, v100
	v_add_f32_e32 v101, v40, v101
	v_add_f32_e32 v100, v37, v100
	v_add_f32_e32 v101, v42, v101
	v_mul_f32_e32 v48, v97, v48
	ds_add_f32 v99, v100
	ds_add_f32 v99, v101 offset:4
	ds_add_f32 v99, v42 offset:8
	v_add_f32_e32 v100, v41, v43
	v_add_f32_e32 v101, v45, v46
	v_cndmask_b32_e32 v48, 0, v48, vcc
	v_mul_f32_e32 v49, v97, v49
	v_cmp_le_u32_e32 vcc, v98, v94
	v_add_f32_e32 v100, v44, v100
	v_add_f32_e32 v101, v47, v101
	v_cndmask_b32_e32 v49, 0, v49, vcc
	v_add_f32_e32 v100, v45, v100
	v_add_f32_e32 v101, v48, v101
	v_add_f32_e32 v101, v49, v101
	ds_add_f32 v99, v100 offset:16
	ds_add_f32 v99, v101 offset:20
	v_cmp_ne_u32_e32 vcc, s2, v98
	s_and_saveexec_b64 s[2:3], vcc
	s_cbranch_execz .LBB0_885
	ds_add_f32 v99, v49 offset:24
	s_branch .LBB0_885
